# NSA item prologue and branch epilogues: remaining packed f32 ops split into scalar pairs
# baseline (speedup 1.0000x reference)
.LBB0_369:
	global_load_ushort v20, v[140:141], off offset:2564
	ds_bpermute_b32 v21, v167, v139
	v_lshlrev_b32_e32 v132, 11, v169
	s_mov_b32 s71, s49
	v_lshlrev_b32_e32 v0, 2, v168
	v_lshl_add_u64 v[18:19], s[44:45], 0, v[132:133]
	s_waitcnt lgkmcnt(0)
	v_add_f32_e32 v21, v139, v21
	ds_bpermute_b32 v22, v166, v21
	v_ashrrev_i32_e32 v1, 31, v0
	v_lshl_add_u64 v[18:19], v[18:19], 0, s[70:71]
	v_lshl_add_u64 v[0:1], v[0:1], 1, v[18:19]
	v_lshlrev_b32_e32 v2, 16, v209
	s_waitcnt lgkmcnt(0)
	v_add_f32_e32 v21, v21, v22
	v_and_b32_e32 v3, 0xffff0000, v209
	v_lshlrev_b32_e32 v4, 16, v208
	v_and_b32_e32 v5, 0xffff0000, v208
	v_lshlrev_b32_e32 v6, 16, v207
	v_and_b32_e32 v7, 0xffff0000, v207
	v_lshlrev_b32_e32 v8, 16, v206
	v_and_b32_e32 v9, 0xffff0000, v206
	v_lshlrev_b32_e32 v10, 16, v204
	v_and_b32_e32 v11, 0xffff0000, v204
	v_lshlrev_b32_e32 v12, 16, v205
	v_and_b32_e32 v13, 0xffff0000, v205
	v_lshlrev_b32_e32 v14, 16, v203
	v_and_b32_e32 v15, 0xffff0000, v203
	v_lshlrev_b32_e32 v16, 16, v202
	v_and_b32_e32 v17, 0xffff0000, v202
	s_mov_b64 s[6:7], 0
	s_waitcnt vmcnt(0)
	v_lshlrev_b32_e32 v20, 16, v20
	v_mul_f32_e32 v20, 0xbfb8aa3b, v20
	v_exp_f32_e32 v20, v20
	s_nop 0
	v_add_f32_e32 v20, 1.0, v20
	v_div_scale_f32 v23, s[0:1], v20, v20, 1.0
	v_rcp_f32_e32 v24, v23
	v_div_scale_f32 v22, vcc, 1.0, v20, 1.0
	v_fma_f32 v25, -v23, v24, 1.0
	v_fmac_f32_e32 v24, v25, v24
	v_mul_f32_e32 v25, v22, v24
	v_fma_f32 v26, -v23, v25, v22
	v_fmac_f32_e32 v25, v26, v24
	v_fma_f32 v22, -v23, v25, v22
	v_div_fmas_f32 v22, v22, v24, v25
	v_div_fixup_f32 v20, v22, v20, 1.0
	v_div_scale_f32 v22, s[0:1], v21, v21, v20
	v_rcp_f32_e32 v23, v22
	v_div_scale_f32 v18, vcc, v20, v21, v20
	v_fma_f32 v19, -v22, v23, 1.0
	v_fmac_f32_e32 v23, v19, v23
	v_mul_f32_e32 v19, v18, v23
	v_fma_f32 v24, -v22, v19, v18
	v_fmac_f32_e32 v19, v24, v23
	v_fma_f32 v18, -v22, v19, v18
	v_div_fmas_f32 v18, v18, v23, v19
	v_div_fixup_f32 v18, v18, v21, v20
	v_cmp_lt_f32_e32 vcc, 0, v21
	s_nop 1
	v_cndmask_b32_e32 v18, 0, v18, vcc
	v_fma_f32 v2, v80, v18, v2
	v_fma_f32 v3, v81, v18, v3
	v_fma_f32 v4, v82, v18, v4
	v_fma_f32 v5, v83, v18, v5
	v_fma_f32 v8, v86, v18, v8
	v_fma_f32 v9, v87, v18, v9
	v_fma_f32 v6, v84, v18, v6
	v_fma_f32 v7, v85, v18, v7
	v_cvt_pk_bf16_f32 v2, v2, v3
	v_cvt_pk_bf16_f32 v3, v4, v5
	v_fma_f32 v12, v90, v18, v12
	v_fma_f32 v13, v91, v18, v13
	v_fma_f32 v10, v88, v18, v10
	v_fma_f32 v11, v89, v18, v11
	v_fma_f32 v16, v94, v18, v16
	v_fma_f32 v17, v95, v18, v17
	v_fma_f32 v14, v92, v18, v14
	v_fma_f32 v15, v93, v18, v15
	v_cvt_pk_bf16_f32 v4, v6, v7
	v_cvt_pk_bf16_f32 v5, v8, v9
	v_cvt_pk_bf16_f32 v6, v10, v11
	v_cvt_pk_bf16_f32 v7, v12, v13
	v_cvt_pk_bf16_f32 v9, v16, v17
	s_nop 0
	v_cvt_pk_bf16_f32 v8, v14, v15
	global_store_dwordx2 v[0:1], v[2:3], off
	global_store_dwordx2 v[0:1], v[4:5], off offset:32
	global_store_dwordx2 v[0:1], v[6:7], off offset:64
	global_store_dwordx2 v[0:1], v[8:9], off offset:96
	global_load_ushort v16, v[136:137], off offset:2564
	ds_bpermute_b32 v17, v167, v138
	v_lshlrev_b32_e32 v2, 16, v201
	v_and_b32_e32 v3, 0xffff0000, v201
	v_lshlrev_b32_e32 v4, 16, v200
	v_and_b32_e32 v5, 0xffff0000, v200
	s_waitcnt lgkmcnt(0)
	v_add_f32_e32 v17, v138, v17
	ds_bpermute_b32 v19, v166, v17
	v_lshlrev_b32_e32 v6, 16, v199
	v_and_b32_e32 v7, 0xffff0000, v199
	v_lshlrev_b32_e32 v8, 16, v198
	v_and_b32_e32 v9, 0xffff0000, v198
	s_waitcnt lgkmcnt(0)
	v_add_f32_e32 v19, v17, v19
	v_lshlrev_b32_e32 v10, 16, v196
	v_and_b32_e32 v11, 0xffff0000, v196
	v_lshlrev_b32_e32 v12, 16, v195
	v_and_b32_e32 v13, 0xffff0000, v195
	v_lshlrev_b32_e32 v14, 16, v197
	v_and_b32_e32 v15, 0xffff0000, v197
	s_waitcnt vmcnt(0)
	v_lshlrev_b32_e32 v16, 16, v16
	v_mul_f32_e32 v16, 0xbfb8aa3b, v16
	v_exp_f32_e32 v18, v16
	v_lshlrev_b32_e32 v16, 16, v194
	v_add_f32_e32 v18, 1.0, v18
	v_div_scale_f32 v20, s[0:1], v18, v18, 1.0
	v_rcp_f32_e32 v21, v20
	v_div_scale_f32 v17, vcc, 1.0, v18, 1.0
	v_fma_f32 v22, -v20, v21, 1.0
	v_fmac_f32_e32 v21, v22, v21
	v_mul_f32_e32 v22, v17, v21
	v_fma_f32 v23, -v20, v22, v17
	v_fmac_f32_e32 v22, v23, v21
	v_fma_f32 v17, -v20, v22, v17
	v_div_fmas_f32 v17, v17, v21, v22
	v_div_fixup_f32 v18, v17, v18, 1.0
	v_div_scale_f32 v20, s[0:1], v19, v19, v18
	v_rcp_f32_e32 v21, v20
	v_div_scale_f32 v22, vcc, v18, v19, v18
	v_and_b32_e32 v17, 0xffff0000, v194
	v_fma_f32 v23, -v20, v21, 1.0
	v_fmac_f32_e32 v21, v23, v21
	v_mul_f32_e32 v23, v22, v21
	v_fma_f32 v24, -v20, v23, v22
	v_fmac_f32_e32 v23, v24, v21
	v_fma_f32 v20, -v20, v23, v22
	v_div_fmas_f32 v20, v20, v21, v23
	v_div_fixup_f32 v18, v20, v19, v18
	v_cmp_lt_f32_e32 vcc, 0, v19
	s_nop 1
	v_cndmask_b32_e32 v18, 0, v18, vcc
	v_fma_f32 v2, v64, v18, v2
	v_fma_f32 v3, v65, v18, v3
	v_fma_f32 v4, v66, v18, v4
	v_fma_f32 v5, v67, v18, v5
	v_fma_f32 v8, v70, v18, v8
	v_fma_f32 v9, v71, v18, v9
	v_fma_f32 v6, v68, v18, v6
	v_fma_f32 v7, v69, v18, v7
	v_cvt_pk_bf16_f32 v2, v2, v3
	v_cvt_pk_bf16_f32 v3, v4, v5
	v_fma_f32 v12, v74, v18, v12
	v_fma_f32 v13, v75, v18, v13
	v_fma_f32 v10, v72, v18, v10
	v_fma_f32 v11, v73, v18, v11
	v_fma_f32 v16, v78, v18, v16
	v_fma_f32 v17, v79, v18, v17
	v_fma_f32 v14, v76, v18, v14
	v_fma_f32 v15, v77, v18, v15
	v_cvt_pk_bf16_f32 v4, v6, v7
	v_cvt_pk_bf16_f32 v5, v8, v9
	v_cvt_pk_bf16_f32 v6, v10, v11
	v_cvt_pk_bf16_f32 v7, v12, v13
	v_cvt_pk_bf16_f32 v9, v16, v17
	s_nop 0
	v_cvt_pk_bf16_f32 v8, v14, v15
	global_store_dwordx2 v[0:1], v[2:3], off offset:128
	global_store_dwordx2 v[0:1], v[4:5], off offset:160
	global_store_dwordx2 v[0:1], v[6:7], off offset:192
	global_store_dwordx2 v[0:1], v[8:9], off offset:224
	global_load_ushort v16, v[136:137], off offset:2570
	ds_bpermute_b32 v17, v167, v143
	v_lshlrev_b32_e32 v2, 16, v193
	v_and_b32_e32 v3, 0xffff0000, v193
	v_lshlrev_b32_e32 v4, 16, v192
	v_and_b32_e32 v5, 0xffff0000, v192
	s_waitcnt lgkmcnt(0)
	v_add_f32_e32 v17, v143, v17
	ds_bpermute_b32 v19, v166, v17
	v_lshlrev_b32_e32 v6, 16, v191
	v_and_b32_e32 v7, 0xffff0000, v191
	v_lshlrev_b32_e32 v8, 16, v190
	v_and_b32_e32 v9, 0xffff0000, v190
	s_waitcnt lgkmcnt(0)
	v_add_f32_e32 v19, v17, v19
	v_lshlrev_b32_e32 v10, 16, v188
	v_and_b32_e32 v11, 0xffff0000, v188
	v_lshlrev_b32_e32 v12, 16, v187
	v_and_b32_e32 v13, 0xffff0000, v187
	v_lshlrev_b32_e32 v14, 16, v189
	v_and_b32_e32 v15, 0xffff0000, v189
	s_waitcnt vmcnt(0)
	v_lshlrev_b32_e32 v16, 16, v16
	v_mul_f32_e32 v16, 0xbfb8aa3b, v16
	v_exp_f32_e32 v18, v16
	v_lshlrev_b32_e32 v16, 16, v186
	v_add_f32_e32 v18, 1.0, v18
	v_div_scale_f32 v20, s[0:1], v18, v18, 1.0
	v_rcp_f32_e32 v21, v20
	v_div_scale_f32 v17, vcc, 1.0, v18, 1.0
	v_fma_f32 v22, -v20, v21, 1.0
	v_fmac_f32_e32 v21, v22, v21
	v_mul_f32_e32 v22, v17, v21
	v_fma_f32 v23, -v20, v22, v17
	v_fmac_f32_e32 v22, v23, v21
	v_fma_f32 v17, -v20, v22, v17
	v_div_fmas_f32 v17, v17, v21, v22
	v_div_fixup_f32 v18, v17, v18, 1.0
	v_div_scale_f32 v20, s[0:1], v19, v19, v18
	v_rcp_f32_e32 v21, v20
	v_div_scale_f32 v22, vcc, v18, v19, v18
	v_and_b32_e32 v17, 0xffff0000, v186
	v_fma_f32 v23, -v20, v21, 1.0
	v_fmac_f32_e32 v21, v23, v21
	v_mul_f32_e32 v23, v22, v21
	v_fma_f32 v24, -v20, v23, v22
	v_fmac_f32_e32 v23, v24, v21
	v_fma_f32 v20, -v20, v23, v22
	v_div_fmas_f32 v20, v20, v21, v23
	v_div_fixup_f32 v18, v20, v19, v18
	v_cmp_lt_f32_e32 vcc, 0, v19
	s_nop 1
	v_cndmask_b32_e32 v18, 0, v18, vcc
	v_fma_f32 v2, v48, v18, v2
	v_fma_f32 v3, v49, v18, v3
	v_fma_f32 v4, v50, v18, v4
	v_fma_f32 v5, v51, v18, v5
	v_fma_f32 v8, v54, v18, v8
	v_fma_f32 v9, v55, v18, v9
	v_fma_f32 v6, v52, v18, v6
	v_fma_f32 v7, v53, v18, v7
	v_cvt_pk_bf16_f32 v2, v2, v3
	v_cvt_pk_bf16_f32 v3, v4, v5
	v_fma_f32 v12, v58, v18, v12
	v_fma_f32 v13, v59, v18, v13
	v_fma_f32 v10, v56, v18, v10
	v_fma_f32 v11, v57, v18, v11
	v_fma_f32 v16, v62, v18, v16
	v_fma_f32 v17, v63, v18, v17
	v_fma_f32 v14, v60, v18, v14
	v_fma_f32 v15, v61, v18, v15
	v_cvt_pk_bf16_f32 v4, v6, v7
	v_cvt_pk_bf16_f32 v5, v8, v9
	v_cvt_pk_bf16_f32 v6, v10, v11
	v_cvt_pk_bf16_f32 v7, v12, v13
	v_cvt_pk_bf16_f32 v9, v16, v17
	s_nop 0
	v_cvt_pk_bf16_f32 v8, v14, v15
	global_store_dwordx2 v[0:1], v[2:3], off offset:256
	global_store_dwordx2 v[0:1], v[4:5], off offset:288
	global_store_dwordx2 v[0:1], v[6:7], off offset:320
	global_store_dwordx2 v[0:1], v[8:9], off offset:352
	global_load_ushort v16, v[136:137], off offset:2576
	ds_bpermute_b32 v17, v167, v142
	v_lshlrev_b32_e32 v2, 16, v184
	v_and_b32_e32 v3, 0xffff0000, v184
	v_lshlrev_b32_e32 v4, 16, v185
	v_and_b32_e32 v5, 0xffff0000, v185
	s_waitcnt lgkmcnt(0)
	v_add_f32_e32 v17, v142, v17
	ds_bpermute_b32 v19, v166, v17
	v_lshlrev_b32_e32 v6, 16, v178
	v_and_b32_e32 v7, 0xffff0000, v178
	v_lshlrev_b32_e32 v8, 16, v179
	v_and_b32_e32 v9, 0xffff0000, v179
	s_waitcnt lgkmcnt(0)
	v_add_f32_e32 v19, v17, v19
	v_lshlrev_b32_e32 v10, 16, v176
	v_and_b32_e32 v11, 0xffff0000, v176
	v_lshlrev_b32_e32 v12, 16, v177
	v_and_b32_e32 v13, 0xffff0000, v177
	v_lshlrev_b32_e32 v14, 16, v175
	v_and_b32_e32 v15, 0xffff0000, v175
	s_waitcnt vmcnt(0)
	v_lshlrev_b32_e32 v16, 16, v16
	v_mul_f32_e32 v16, 0xbfb8aa3b, v16
	v_exp_f32_e32 v18, v16
	v_lshlrev_b32_e32 v16, 16, v174
	v_add_f32_e32 v18, 1.0, v18
	v_div_scale_f32 v20, s[0:1], v18, v18, 1.0
	v_rcp_f32_e32 v21, v20
	v_div_scale_f32 v17, vcc, 1.0, v18, 1.0
	v_fma_f32 v22, -v20, v21, 1.0
	v_fmac_f32_e32 v21, v22, v21
	v_mul_f32_e32 v22, v17, v21
	v_fma_f32 v23, -v20, v22, v17
	v_fmac_f32_e32 v22, v23, v21
	v_fma_f32 v17, -v20, v22, v17
	v_div_fmas_f32 v17, v17, v21, v22
	v_div_fixup_f32 v18, v17, v18, 1.0
	v_div_scale_f32 v20, s[0:1], v19, v19, v18
	v_rcp_f32_e32 v21, v20
	v_div_scale_f32 v22, vcc, v18, v19, v18
	v_and_b32_e32 v17, 0xffff0000, v174
	v_fma_f32 v23, -v20, v21, 1.0
	v_fmac_f32_e32 v21, v23, v21
	v_mul_f32_e32 v23, v22, v21
	v_fma_f32 v24, -v20, v23, v22
	v_fmac_f32_e32 v23, v24, v21
	v_fma_f32 v20, -v20, v23, v22
	v_div_fmas_f32 v20, v20, v21, v23
	v_div_fixup_f32 v18, v20, v19, v18
	v_cmp_lt_f32_e32 vcc, 0, v19
	s_nop 1
	v_cndmask_b32_e32 v18, 0, v18, vcc
	v_fma_f32 v2, v32, v18, v2
	v_fma_f32 v3, v33, v18, v3
	v_fma_f32 v4, v34, v18, v4
	v_fma_f32 v5, v35, v18, v5
	v_fma_f32 v8, v38, v18, v8
	v_fma_f32 v9, v39, v18, v9
	v_fma_f32 v6, v36, v18, v6
	v_fma_f32 v7, v37, v18, v7
	v_cvt_pk_bf16_f32 v2, v2, v3
	v_cvt_pk_bf16_f32 v3, v4, v5
	v_fma_f32 v12, v46, v18, v12
	v_fma_f32 v13, v47, v18, v13
	v_fma_f32 v10, v44, v18, v10
	v_fma_f32 v11, v45, v18, v11
	v_fma_f32 v16, v42, v18, v16
	v_fma_f32 v17, v43, v18, v17
	v_fma_f32 v14, v40, v18, v14
	v_fma_f32 v15, v41, v18, v15
	v_cvt_pk_bf16_f32 v4, v6, v7
	v_cvt_pk_bf16_f32 v5, v8, v9
	v_cvt_pk_bf16_f32 v6, v10, v11
	v_cvt_pk_bf16_f32 v7, v12, v13
	v_cvt_pk_bf16_f32 v9, v16, v17
	s_nop 0
	v_cvt_pk_bf16_f32 v8, v14, v15
	global_store_dwordx2 v[0:1], v[2:3], off offset:384
	global_store_dwordx2 v[0:1], v[4:5], off offset:416
	global_store_dwordx2 v[0:1], v[6:7], off offset:448
	global_store_dwordx2 v[0:1], v[8:9], off offset:480

.LBB0_375:
	s_or_b64 exec, exec, s[6:7]
	v_readfirstlane_b32 s1, v0
	s_cmpk_gt_u32 s1, 0x1ff
	s_mov_b64 s[6:7], -1
	s_cbranch_scc1 .LBB0_370
	s_lshl_b32 s0, s1, 4
	s_and_b32 s0, s0, 0xff0
	v_mov_b32_e32 v152, v182
	s_xor_b32 s80, s0, 0xff0
	v_and_b32_e32 v128, 15, v152
	v_or_b32_e32 v134, s80, v128
	v_ashrrev_i32_e32 v168, 4, v152
	v_or_b32_e32 v169, s97, v134
	v_mov_b64_e32 v[0:1], s[34:35]
	v_mad_u64_u32 v[136:137], s[6:7], v169, s89, v[0:1]
	v_lshlrev_b32_e32 v130, 3, v168
	v_ashrrev_i32_e32 v131, 31, v130
	s_and_b32 s6, s1, 0x100
	v_lshl_add_u64 v[8:9], v[130:131], 1, v[136:137]
	s_lshl_b32 s70, s6, 1
	s_mov_b32 s71, s49
	v_lshl_add_u64 v[4:5], v[8:9], 0, s[70:71]
	global_load_dwordx4 v[0:3], v[4:5], off
	s_nop 0
	global_load_dwordx4 v[4:7], v[4:5], off offset:64
	s_lshr_b32 s22, s1, 8
	s_lshl_b32 s1, s22, 2
	s_or_b32 s6, s1, 1
	s_lshl_b32 s48, s6, 7
	v_lshl_add_u64 v[14:15], v[8:9], 0, s[48:49]
	global_load_dwordx4 v[10:13], v[14:15], off
	s_nop 0
	global_load_dwordx4 v[14:17], v[14:15], off offset:64
	v_lshl_add_u64 v[18:19], v[130:131], 2, s[42:43]
	global_load_dwordx4 v[36:39], v[18:19], off
	global_load_dwordx4 v[32:35], v[18:19], off offset:128
	global_load_dwordx4 v[28:31], v[18:19], off offset:16
	global_load_dwordx4 v[24:27], v[18:19], off offset:144
	v_cmp_lt_i32_e32 vcc, v162, v163
	s_or_b32 s7, s1, 2
	s_lshl_b32 s48, s7, 7
	v_cndmask_b32_e32 v18, v181, v162, vcc
	v_lshlrev_b32_e32 v167, 2, v18
	v_cmp_lt_i32_e32 vcc, v164, v163
	s_or_b32 s8, s1, 3
	s_add_i32 s1, s1, 4
	v_mov_b32_e32 v129, 0
	v_lshl_add_u32 v131, v152, 2, s79
	v_and_b32_e32 v138, -16, v152
	v_lshlrev_b32_e32 v132, 4, v128
	s_mul_i32 s74, s22, 24
	s_mul_i32 s72, s6, 6
	v_ashrrev_i32_e32 v139, 31, v138
	v_mov_b32_e32 v189, 0
	v_mov_b32_e32 v187, 0
	v_mov_b32_e32 v188, 0
	v_mov_b32_e32 v157, 0
	v_mov_b32_e32 v158, 0
	v_mov_b32_e32 v156, 0
	v_mov_b32_e32 v155, 0
	v_mov_b32_e32 v190, 0
	v_mov_b32_e32 v191, 0
	v_mov_b32_e32 v185, 0
	v_mov_b32_e32 v186, 0
	v_mov_b32_e32 v159, 0
	v_mov_b32_e32 v160, 0
	v_mov_b32_e32 v154, 0
	v_mov_b32_e32 v153, 0
	v_mov_b32_e32 v192, 0
	v_mov_b32_e32 v193, 0
	v_mov_b32_e32 v178, 0
	v_mov_b32_e32 v179, 0
	v_mov_b32_e32 v161, 0
	v_mov_b32_e32 v174, 0
	v_mov_b32_e32 v151, 0
	v_mov_b32_e32 v150, 0
	v_mov_b32_e32 v194, 0
	v_mov_b32_e32 v195, 0
	v_mov_b32_e32 v177, 0
	v_mov_b32_e32 v184, 0
	v_mov_b32_e32 v175, 0
	v_mov_b32_e32 v176, 0
	v_mov_b32_e32 v149, 0
	v_mov_b32_e32 v148, 0
	s_waitcnt vmcnt(7)
	v_lshlrev_b32_e32 v18, 16, v0
	s_waitcnt vmcnt(6)
	v_lshlrev_b32_e32 v20, 16, v4
	v_and_b32_e32 v21, 0xffff0000, v4
	v_and_b32_e32 v19, 0xffff0000, v0
	v_and_b32_e32 v4, 0xffff0000, v5
	v_lshlrev_b32_e32 v5, 16, v5
	v_mul_f32_e32 v42, v20, v20
	v_mul_f32_e32 v43, v21, v21
	v_and_b32_e32 v0, 0xffff0000, v1
	v_lshlrev_b32_e32 v1, 16, v1
	v_mul_f32_e32 v44, v4, v4
	v_mul_f32_e32 v45, v5, v5
	v_fma_f32 v42, v18, v18, v42
	v_fma_f32 v43, v19, v19, v43
	v_and_b32_e32 v40, 0xffff0000, v6
	v_lshlrev_b32_e32 v41, 16, v6
	v_fma_f32 v44, v0, v0, v44
	v_fma_f32 v45, v1, v1, v45
	v_add_f32_e32 v42, v42, v43
	v_and_b32_e32 v22, 0xffff0000, v2
	v_lshlrev_b32_e32 v23, 16, v2
	v_mul_f32_e32 v46, v40, v40
	v_mul_f32_e32 v47, v41, v41
	v_add_f32_e32 v42, v45, v42
	v_and_b32_e32 v6, 0xffff0000, v7
	v_lshlrev_b32_e32 v7, 16, v7
	v_fma_f32 v46, v22, v22, v46
	v_fma_f32 v47, v23, v23, v47
	v_add_f32_e32 v42, v44, v42
	v_and_b32_e32 v2, 0xffff0000, v3
	v_lshlrev_b32_e32 v3, 16, v3
	v_mul_f32_e32 v48, v6, v6
	v_mul_f32_e32 v49, v7, v7
	v_add_f32_e32 v42, v47, v42
	v_fma_f32 v48, v2, v2, v48
	v_fma_f32 v49, v3, v3, v49
	v_add_f32_e32 v42, v46, v42
	v_add_f32_e32 v42, v49, v42
	v_add_f32_e32 v42, v48, v42
	ds_bpermute_b32 v43, v167, v42
	v_cndmask_b32_e32 v44, v181, v164, vcc
	v_lshlrev_b32_e32 v166, 2, v44
	s_waitcnt vmcnt(5)
	v_lshlrev_b32_e32 v44, 16, v10
	v_and_b32_e32 v45, 0xffff0000, v10
	s_waitcnt lgkmcnt(0)
	v_add_f32_e32 v42, v42, v43
	ds_bpermute_b32 v43, v166, v42
	s_waitcnt vmcnt(4)
	v_lshlrev_b32_e32 v46, 16, v14
	v_and_b32_e32 v47, 0xffff0000, v14
	s_waitcnt lgkmcnt(0)
	v_add_f32_e32 v10, v42, v43
	v_fmamk_f32 v10, v10, 0x3c800000, v135
	v_mul_f32_e32 v14, 0x4b800000, v10
	v_cmp_gt_f32_e32 vcc, s90, v10
	v_mul_f32_e32 v42, v46, v46
	v_mul_f32_e32 v43, v47, v47
	s_nop 0
	v_cndmask_b32_e32 v10, v10, v14, vcc
	v_rsq_f32_e32 v14, v10
	v_fma_f32 v48, v44, v44, v42
	v_fma_f32 v49, v45, v45, v43
	v_and_b32_e32 v10, 0xffff0000, v11
	v_lshlrev_b32_e32 v11, 16, v11
	v_mul_f32_e32 v42, 0x45800000, v14
	v_cndmask_b32_e32 v14, v14, v42, vcc
	v_mul_f32_e32 v14, 0x3e38aa3b, v14
	s_waitcnt vmcnt(3)
	v_mul_f32_e32 v52, v38, v14
	v_mul_f32_e32 v54, v39, v14
	v_mul_f32_e32 v42, v36, v14
	s_waitcnt vmcnt(2)
	v_mul_f32_e32 v43, v32, v14
	v_mul_f32_e32 v50, v37, v14
	v_mul_f32_e32 v51, v33, v14
	v_mul_f32_e32 v52, v52, v1
	v_mul_f32_e32 v54, v54, v0
	v_lshl_add_u64 v[0:1], v[8:9], 0, s[48:49]
	v_mul_f32_e32 v63, v42, v18
	v_mul_f32_e32 v64, v43, v20
	v_mul_f32_e32 v65, v50, v19
	v_mul_f32_e32 v66, v51, v21
	global_load_dwordx4 v[18:21], v[0:1], off
	s_waitcnt vmcnt(1)
	v_mul_f32_e32 v57, v24, v14
	v_mul_f32_e32 v59, v25, v14
	v_mul_f32_e32 v53, v34, v14
	v_mul_f32_e32 v55, v35, v14
	v_mul_f32_e32 v56, v28, v14
	v_mul_f32_e32 v58, v29, v14
	v_mul_f32_e32 v60, v30, v14
	v_mul_f32_e32 v61, v26, v14
	v_mul_f32_e32 v62, v31, v14
	v_mul_f32_e32 v14, v27, v14
	v_mul_f32_e32 v57, v57, v41
	v_mul_f32_e32 v59, v59, v40
	global_load_dwordx4 v[40:43], v[0:1], off offset:64
	v_mul_f32_e32 v7, v61, v7
	v_mul_f32_e32 v61, v62, v2
	v_mul_f32_e32 v62, v14, v6
	v_and_b32_e32 v14, 0xffff0000, v15
	v_lshlrev_b32_e32 v15, 16, v15
	v_mul_f32_e32 v0, v14, v14
	v_mul_f32_e32 v1, v15, v15
	v_and_b32_e32 v50, 0xffff0000, v16
	v_fma_f32 v0, v10, v10, v0
	v_fma_f32 v1, v11, v11, v1
	v_lshlrev_b32_e32 v51, 16, v16
	v_add_f32_e32 v6, v48, v49
	v_mul_f32_e32 v56, v56, v23
	v_mul_f32_e32 v58, v58, v22
	v_mul_f32_e32 v60, v60, v3
	v_and_b32_e32 v22, 0xffff0000, v12
	v_lshlrev_b32_e32 v23, 16, v12
	v_mul_f32_e32 v2, v50, v50
	v_mul_f32_e32 v3, v51, v51
	v_add_f32_e32 v1, v1, v6
	v_fma_f32 v2, v22, v22, v2
	v_fma_f32 v3, v23, v23, v3
	v_and_b32_e32 v16, 0xffff0000, v17
	v_lshlrev_b32_e32 v17, 16, v17
	v_add_f32_e32 v0, v0, v1
	v_mul_f32_e32 v53, v53, v5
	v_mul_f32_e32 v55, v55, v4
	v_and_b32_e32 v12, 0xffff0000, v13
	v_lshlrev_b32_e32 v13, 16, v13
	v_mul_f32_e32 v4, v16, v16
	v_mul_f32_e32 v5, v17, v17
	v_add_f32_e32 v0, v3, v0
	v_fma_f32 v4, v12, v12, v4
	v_fma_f32 v5, v13, v13, v5
	v_add_f32_e32 v0, v2, v0
	v_add_f32_e32 v0, v5, v0
	v_add_f32_e32 v3, v4, v0
	ds_bpermute_b32 v4, v167, v3
	v_cvt_f32_u32_e32 v6, s6
	v_cvt_pk_bf16_f32 v1, v52, v54
	v_cvt_pk_bf16_f32 v2, v56, v58
	v_cvt_pk_bf16_f32 v7, v7, v62
	s_waitcnt lgkmcnt(0)
	v_add_f32_e32 v48, v3, v4
	ds_bpermute_b32 v49, v166, v48
	v_exp_f32_e64 v52, -v6
	v_cvt_pk_bf16_f32 v3, v60, v61
	v_cvt_pk_bf16_f32 v0, v63, v65
	v_cvt_pk_bf16_f32 v4, v64, v66
	s_waitcnt lgkmcnt(0)
	v_add_f32_e32 v6, v48, v49
	v_fmamk_f32 v6, v6, 0x3c800000, v135
	v_mul_f32_e32 v48, 0x4b800000, v6
	v_cmp_gt_f32_e32 vcc, s90, v6
	s_lshl_b32 s48, s8, 7
	v_lshl_add_u64 v[8:9], v[8:9], 0, s[48:49]
	v_cndmask_b32_e32 v6, v6, v48, vcc
	v_rsq_f32_e32 v48, v6
	v_cvt_pk_bf16_f32 v6, v57, v59
	v_cvt_pk_bf16_f32 v5, v53, v55
	v_mul_f32_e32 v170, 0x3fb8aa3b, v52
	v_mul_f32_e32 v49, 0x45800000, v48
	v_cndmask_b32_e32 v48, v48, v49, vcc
	v_mul_f32_e32 v48, 0x3e38aa3b, v48
	v_mul_f32_e32 v49, v36, v48
	v_mul_f32_e32 v56, v49, v44
	v_mul_f32_e32 v44, v32, v48
	v_mul_f32_e32 v57, v44, v46
	v_mul_f32_e32 v44, v37, v48
	v_mul_f32_e32 v58, v44, v45
	v_mul_f32_e32 v44, v33, v48
	v_mul_f32_e32 v59, v44, v47
	v_mul_f32_e32 v44, v38, v48
	v_mul_f32_e32 v60, v44, v11
	v_mul_f32_e32 v11, v34, v48
	v_mul_f32_e32 v61, v11, v15
	v_mul_f32_e32 v11, v39, v48
	v_mul_f32_e32 v62, v11, v10
	v_mul_f32_e32 v10, v35, v48
	v_mul_f32_e32 v63, v10, v14
	v_mul_f32_e32 v10, v28, v48
	v_mul_f32_e32 v64, v10, v23
	v_mul_f32_e32 v10, v24, v48
	v_mul_f32_e32 v65, v10, v51
	v_mul_f32_e32 v10, v29, v48
	v_mul_f32_e32 v66, v10, v22
	v_mul_f32_e32 v10, v25, v48
	v_mul_f32_e32 v67, v10, v50
	v_mul_f32_e32 v10, v30, v48
	v_mul_f32_e32 v68, v10, v13
	v_mul_f32_e32 v10, v26, v48
	v_mul_f32_e32 v69, v10, v17
	v_mul_f32_e32 v10, v31, v48
	v_mul_f32_e32 v70, v10, v12
	v_mul_f32_e32 v10, v27, v48
	v_mul_f32_e32 v71, v10, v16
	s_waitcnt vmcnt(1)
	v_lshlrev_b32_e32 v22, 16, v18
	v_and_b32_e32 v23, 0xffff0000, v18
	v_and_b32_e32 v50, 0xffff0000, v19
	v_lshlrev_b32_e32 v51, 16, v19
	global_load_dwordx4 v[16:19], v[8:9], off
	global_load_dwordx4 v[44:47], v[8:9], off offset:64
	s_waitcnt vmcnt(2)
	v_lshlrev_b32_e32 v48, 16, v40
	v_and_b32_e32 v49, 0xffff0000, v40
	v_mul_f32_e32 v10, v48, v48
	v_mul_f32_e32 v11, v49, v49
	v_and_b32_e32 v40, 0xffff0000, v41
	v_lshlrev_b32_e32 v41, 16, v41
	v_fma_f32 v10, v22, v22, v10
	v_fma_f32 v11, v23, v23, v11
	v_mul_f32_e32 v8, v40, v40
	v_mul_f32_e32 v9, v41, v41
	v_and_b32_e32 v54, 0xffff0000, v42
	v_fma_f32 v8, v50, v50, v8
	v_fma_f32 v9, v51, v51, v9
	v_lshlrev_b32_e32 v55, 16, v42
	v_add_f32_e32 v10, v10, v11
	v_and_b32_e32 v52, 0xffff0000, v20
	v_lshlrev_b32_e32 v53, 16, v20
	v_mul_f32_e32 v12, v54, v54
	v_mul_f32_e32 v13, v55, v55
	v_add_f32_e32 v9, v9, v10
	v_fma_f32 v12, v52, v52, v12
	v_fma_f32 v13, v53, v53, v13
	v_and_b32_e32 v42, 0xffff0000, v43
	v_lshlrev_b32_e32 v43, 16, v43
	v_add_f32_e32 v8, v8, v9
	v_and_b32_e32 v20, 0xffff0000, v21
	v_lshlrev_b32_e32 v21, 16, v21
	v_mul_f32_e32 v14, v42, v42
	v_mul_f32_e32 v15, v43, v43
	v_add_f32_e32 v8, v13, v8
	v_fma_f32 v14, v20, v20, v14
	v_fma_f32 v15, v21, v21, v15
	v_add_f32_e32 v8, v12, v8
	v_add_f32_e32 v8, v15, v8
	v_add_f32_e32 v11, v14, v8
	ds_bpermute_b32 v12, v167, v11
	v_cvt_pk_bf16_f32 v8, v56, v58
	v_cvt_f32_u32_e32 v14, s7
	v_cvt_pk_bf16_f32 v9, v60, v62
	v_cvt_pk_bf16_f32 v13, v61, v63
	s_waitcnt lgkmcnt(0)
	v_add_f32_e32 v15, v11, v12
	ds_bpermute_b32 v56, v166, v15
	v_cvt_pk_bf16_f32 v12, v57, v59
	v_exp_f32_e64 v57, -v14
	v_cvt_pk_bf16_f32 v10, v64, v66
	v_cvt_pk_bf16_f32 v11, v68, v70
	s_waitcnt lgkmcnt(0)
	v_add_f32_e32 v14, v15, v56
	v_fmamk_f32 v14, v14, 0x3c800000, v135
	v_mul_f32_e32 v15, 0x4b800000, v14
	v_cmp_gt_f32_e32 vcc, s90, v14
	v_mul_f32_e32 v171, 0x3fb8aa3b, v57
	ds_write2st64_b32 v131, v129, v129 offset1:1
	ds_write2st64_b32 v131, v129, v129 offset0:2 offset1:3
	ds_write2st64_b32 v131, v129, v129 offset0:4 offset1:5
	ds_write2st64_b32 v131, v129, v129 offset0:6 offset1:7
	ds_write2st64_b32 v131, v129, v129 offset0:8 offset1:9
	ds_write2st64_b32 v131, v129, v129 offset0:10 offset1:11
	ds_write2st64_b32 v131, v129, v129 offset0:12 offset1:13
	ds_write2st64_b32 v131, v129, v129 offset0:14 offset1:15
	v_cndmask_b32_e32 v14, v14, v15, vcc
	v_rsq_f32_e32 v56, v14
	v_cvt_pk_bf16_f32 v14, v65, v67
	v_cvt_pk_bf16_f32 v15, v69, v71
	s_waitcnt lgkmcnt(0)
	s_cmpk_eq_i32 s0, 0xff0
	v_mul_f32_e32 v57, 0x45800000, v56
	v_cndmask_b32_e32 v56, v56, v57, vcc
	v_mul_f32_e32 v56, 0x3e38aa3b, v56
	v_mul_f32_e32 v57, v36, v56
	v_mul_f32_e32 v57, v57, v22
	v_mul_f32_e32 v22, v32, v56
	v_mul_f32_e32 v58, v22, v48
	v_mul_f32_e32 v22, v37, v56
	v_mul_f32_e32 v59, v22, v23
	v_mul_f32_e32 v22, v33, v56
	v_mul_f32_e32 v60, v22, v49
	v_mul_f32_e32 v22, v38, v56
	v_mul_f32_e32 v61, v22, v51
	v_mul_f32_e32 v22, v34, v56
	v_mul_f32_e32 v62, v22, v41
	v_mul_f32_e32 v22, v39, v56
	v_mul_f32_e32 v63, v22, v50
	v_mul_f32_e32 v22, v35, v56
	v_mul_f32_e32 v64, v22, v40
	v_mul_f32_e32 v22, v28, v56
	v_mul_f32_e32 v65, v22, v53
	v_mul_f32_e32 v22, v24, v56
	v_mul_f32_e32 v66, v22, v55
	v_mul_f32_e32 v22, v29, v56
	v_mul_f32_e32 v67, v22, v52
	v_mul_f32_e32 v22, v25, v56
	v_mul_f32_e32 v68, v22, v54
	v_mul_f32_e32 v22, v30, v56
	v_mul_f32_e32 v69, v22, v21
	v_mul_f32_e32 v21, v26, v56
	v_mul_f32_e32 v70, v21, v43
	v_mul_f32_e32 v21, v31, v56
	v_mul_f32_e32 v71, v21, v20
	v_mul_f32_e32 v20, v27, v56
	v_mul_f32_e32 v56, v20, v42
	s_waitcnt vmcnt(0)
	v_lshlrev_b32_e32 v42, 16, v44
	v_and_b32_e32 v43, 0xffff0000, v44
	v_lshlrev_b32_e32 v40, 16, v16
	v_and_b32_e32 v41, 0xffff0000, v16
	v_mul_f32_e32 v20, v42, v42
	v_mul_f32_e32 v21, v43, v43
	v_and_b32_e32 v44, 0xffff0000, v45
	v_lshlrev_b32_e32 v45, 16, v45
	v_fma_f32 v20, v40, v40, v20
	v_fma_f32 v21, v41, v41, v21
	v_and_b32_e32 v48, 0xffff0000, v17
	v_lshlrev_b32_e32 v49, 16, v17
	v_mul_f32_e32 v16, v44, v44
	v_mul_f32_e32 v17, v45, v45
	v_and_b32_e32 v52, 0xffff0000, v46
	v_fma_f32 v16, v48, v48, v16
	v_fma_f32 v17, v49, v49, v17
	v_lshlrev_b32_e32 v53, 16, v46
	v_add_f32_e32 v20, v20, v21
	v_and_b32_e32 v50, 0xffff0000, v18
	v_lshlrev_b32_e32 v51, 16, v18
	v_mul_f32_e32 v22, v52, v52
	v_mul_f32_e32 v23, v53, v53
	v_add_f32_e32 v17, v17, v20
	v_fma_f32 v22, v50, v50, v22
	v_fma_f32 v23, v51, v51, v23
	v_and_b32_e32 v46, 0xffff0000, v47
	v_lshlrev_b32_e32 v47, 16, v47
	v_add_f32_e32 v16, v16, v17
	v_and_b32_e32 v54, 0xffff0000, v19
	v_lshlrev_b32_e32 v55, 16, v19
	v_mul_f32_e32 v18, v46, v46
	v_mul_f32_e32 v19, v47, v47
	v_add_f32_e32 v16, v23, v16
	v_fma_f32 v18, v54, v54, v18
	v_fma_f32 v19, v55, v55, v19
	v_add_f32_e32 v16, v22, v16
	v_add_f32_e32 v16, v19, v16
	v_add_f32_e32 v19, v18, v16
	ds_bpermute_b32 v20, v167, v19
	v_cvt_pk_bf16_f32 v16, v57, v59
	v_cvt_f32_u32_e32 v22, s8
	v_cvt_pk_bf16_f32 v17, v61, v63
	v_cvt_pk_bf16_f32 v18, v65, v67
	s_waitcnt lgkmcnt(0)
	v_add_f32_e32 v23, v19, v20
	ds_bpermute_b32 v57, v166, v23
	v_cvt_pk_bf16_f32 v20, v58, v60
	v_exp_f32_e64 v58, -v22
	v_cvt_pk_bf16_f32 v19, v69, v71
	v_cvt_pk_bf16_f32 v21, v62, v64
	s_waitcnt lgkmcnt(0)
	v_add_f32_e32 v22, v23, v57
	v_fmamk_f32 v22, v22, 0x3c800000, v135
	v_mul_f32_e32 v23, 0x4b800000, v22
	v_cmp_gt_f32_e32 vcc, s90, v22
	v_mul_f32_e32 v172, 0x3fb8aa3b, v58
	s_nop 0
	v_cndmask_b32_e32 v22, v22, v23, vcc
	v_rsq_f32_e32 v57, v22
	v_cvt_pk_bf16_f32 v23, v70, v56
	v_cvt_pk_bf16_f32 v22, v66, v68
	s_nop 0
	v_mul_f32_e32 v56, 0x45800000, v57
	v_cndmask_b32_e32 v56, v57, v56, vcc
	v_mul_f32_e32 v56, 0x3e38aa3b, v56
	v_mul_f32_e32 v36, v36, v56
	v_mul_f32_e32 v24, v24, v56
	v_mul_f32_e32 v36, v36, v40
	v_mul_f32_e32 v40, v24, v53
	v_mul_f32_e32 v24, v29, v56
	v_mul_f32_e32 v37, v37, v56
	v_mul_f32_e32 v29, v24, v50
	v_mul_f32_e32 v24, v25, v56
	v_mul_f32_e32 v37, v37, v41
	v_mul_f32_e32 v41, v24, v52
	v_mul_f32_e32 v24, v30, v56
	v_mul_f32_e32 v32, v32, v56
	v_mul_f32_e32 v30, v24, v55
	v_mul_f32_e32 v24, v26, v56
	v_mul_f32_e32 v32, v32, v42
	v_mul_f32_e32 v42, v24, v47
	v_mul_f32_e32 v24, v31, v56
	v_mul_f32_e32 v33, v33, v56
	v_mul_f32_e32 v31, v24, v54
	v_mul_f32_e32 v24, v27, v56
	v_mul_f32_e32 v33, v33, v43
	v_mul_f32_e32 v43, v24, v46
	v_cvt_pk_bf16_f32 v24, v36, v37
	v_cvt_f32_u32_e32 v36, s1
	v_mul_f32_e32 v28, v28, v56
	v_mul_f32_e32 v28, v28, v51
	v_cvt_pk_bf16_f32 v26, v28, v29
	v_cvt_pk_bf16_f32 v28, v32, v33
	v_exp_f32_e64 v32, -v36
	v_mul_f32_e32 v38, v38, v56
	v_mul_f32_e32 v34, v34, v56
	v_mul_f32_e32 v39, v39, v56
	v_mul_f32_e32 v35, v35, v56
	v_mul_f32_e32 v173, 0x3fb8aa3b, v32
	v_mul_f32_e32 v38, v38, v49
	v_mul_f32_e32 v34, v34, v45
	v_mul_f32_e32 v39, v39, v48
	v_mul_f32_e32 v35, v35, v44
	v_cvt_pk_bf16_f32 v25, v38, v39
	v_cvt_pk_bf16_f32 v27, v30, v31
	v_cvt_pk_bf16_f32 v29, v34, v35
	v_cvt_pk_bf16_f32 v30, v40, v41
	v_cvt_pk_bf16_f32 v31, v42, v43
	s_cbranch_scc1 .LBB0_386
	s_or_b32 s1, s22, s96
	s_lshr_b32 s0, s0, 4
	s_lshl_b32 s1, s1, 15
	s_sub_i32 s0, 0x11e, s0
	s_add_u32 s6, s83, s1
	s_addc_u32 s7, s84, 0
	v_lshl_add_u64 v[32:33], v[138:139], 4, s[6:7]
	s_add_i32 s6, s80, 0xffffff71
	v_lshl_add_u64 v[140:141], v[32:33], 0, v[132:133]
	v_lshlrev_b32_e32 v153, 7, v168
	v_add_u32_e32 v32, s6, v128
	s_lshr_b32 s0, s0, 5
	v_sub_u32_e32 v154, v32, v153
	v_add_u32_e32 v36, 0x8f, v153
	v_mov_b32_e32 v33, 0
	s_mov_b32 s18, 2
	v_mov_b32_e32 v37, v154
	s_mov_b32 s20, s0
	v_mov_b32_e32 v34, 0
	v_mov_b32_e32 v32, 0
	v_mov_b32_e32 v35, 0

.LBB0_400:
	s_mov_b32 s75, s49
	v_lshl_add_u64 v[140:141], v[136:137], 0, s[74:75]
	s_mov_b32 s73, s49
	v_lshl_add_u64 v[136:137], v[136:137], 0, s[72:73]
	global_load_ushort v120, v[140:141], off offset:2562
	global_load_ushort v121, v[136:137], off offset:2562
	global_load_ushort v124, v[136:137], off offset:2568
	global_load_ushort v125, v[136:137], off offset:2574
	ds_bpermute_b32 v122, v167, v147
	ds_bpermute_b32 v123, v167, v146
	v_lshlrev_b32_e32 v100, 16, v129
	v_and_b32_e32 v101, 0xffff0000, v129
	v_lshlrev_b32_e32 v118, 16, v185
	s_waitcnt lgkmcnt(1)
	v_add_f32_e32 v122, v147, v122
	ds_bpermute_b32 v126, v166, v122
	s_waitcnt lgkmcnt(1)
	v_add_f32_e32 v123, v146, v123
	ds_bpermute_b32 v127, v166, v123
	v_and_b32_e32 v119, 0xffff0000, v185
	v_lshlrev_b32_e32 v96, 16, v189
	s_waitcnt lgkmcnt(1)
	v_add_f32_e32 v122, v122, v126
	v_and_b32_e32 v97, 0xffff0000, v189
	s_waitcnt lgkmcnt(0)
	v_add_f32_e32 v123, v123, v127
	v_lshlrev_b32_e32 v102, 16, v193
	v_and_b32_e32 v103, 0xffff0000, v193
	v_lshlrev_b32_e32 v106, 16, v195
	v_and_b32_e32 v107, 0xffff0000, v195
	v_lshlrev_b32_e32 v116, 16, v186
	v_and_b32_e32 v117, 0xffff0000, v186
	v_lshlrev_b32_e32 v112, 16, v188
	v_and_b32_e32 v113, 0xffff0000, v188
	v_lshlrev_b32_e32 v110, 16, v194
	v_and_b32_e32 v111, 0xffff0000, v194
	v_lshlrev_b32_e32 v108, 16, v192
	v_and_b32_e32 v109, 0xffff0000, v192
	v_lshlrev_b32_e32 v104, 16, v190
	v_and_b32_e32 v105, 0xffff0000, v190
	v_lshlrev_b32_e32 v114, 16, v187
	v_and_b32_e32 v115, 0xffff0000, v187
	v_lshlrev_b32_e32 v98, 16, v191
	v_and_b32_e32 v99, 0xffff0000, v191
	v_mov_b32_e32 v139, 0
	s_waitcnt vmcnt(3)
	v_lshlrev_b32_e32 v120, 16, v120
	v_mul_f32_e32 v120, 0xbfb8aa3b, v120
	v_exp_f32_e32 v120, v120
	s_waitcnt vmcnt(2)
	v_lshlrev_b32_e32 v121, 16, v121
	v_mul_f32_e32 v121, 0xbfb8aa3b, v121
	v_exp_f32_e32 v121, v121
	v_add_f32_e32 v120, 1.0, v120
	v_div_scale_f32 v126, s[0:1], v120, v120, 1.0
	v_rcp_f32_e32 v131, v126
	v_div_scale_f32 v127, vcc, 1.0, v120, 1.0
	v_add_f32_e32 v121, 1.0, v121
	v_fma_f32 v147, -v126, v131, 1.0
	v_fmac_f32_e32 v131, v147, v131
	v_mul_f32_e32 v147, v127, v131
	v_div_scale_f32 v129, s[0:1], v121, v121, 1.0
	v_fma_f32 v180, -v126, v147, v127
	v_rcp_f32_e32 v138, v129
	v_fmac_f32_e32 v147, v180, v131
	v_fma_f32 v126, -v126, v147, v127
	v_div_fmas_f32 v126, v126, v131, v147
	v_div_fixup_f32 v120, v126, v120, 1.0
	v_fma_f32 v152, -v129, v138, 1.0
	v_div_scale_f32 v126, s[0:1], v122, v122, v120
	v_div_scale_f32 v146, s[6:7], 1.0, v121, 1.0
	v_fmac_f32_e32 v138, v152, v138
	v_rcp_f32_e32 v127, v126
	v_mul_f32_e32 v152, v146, v138
	v_fma_f32 v185, -v129, v152, v146
	v_fmac_f32_e32 v152, v185, v138
	v_fma_f32 v129, -v129, v152, v146
	v_fma_f32 v146, -v126, v127, 1.0
	v_div_scale_f32 v131, vcc, v120, v122, v120
	v_fmac_f32_e32 v127, v146, v127
	v_mul_f32_e32 v146, v131, v127
	v_fma_f32 v147, -v126, v146, v131
	v_fmac_f32_e32 v146, v147, v127
	v_fma_f32 v126, -v126, v146, v131
	v_div_fmas_f32 v126, v126, v127, v146
	s_mov_b64 vcc, s[6:7]
	v_div_fixup_f32 v120, v126, v122, v120
	v_div_fmas_f32 v126, v129, v138, v152
	v_cmp_lt_f32_e32 vcc, 0, v122
	v_div_fixup_f32 v121, v126, v121, 1.0
	v_mov_b32_e32 v138, v139
	v_cndmask_b32_e32 v120, 0, v120, vcc
	v_fma_f32 v92, v92, v120, v96
	v_fma_f32 v93, v93, v120, v97
	v_fma_f32 v84, v84, v120, v102
	v_fma_f32 v85, v85, v120, v103
	v_div_scale_f32 v96, s[0:1], v123, v123, v121
	v_cvt_pk_bf16_f32 v204, v84, v85
	v_rcp_f32_e32 v84, v96
	v_fma_f32 v80, v80, v120, v106
	v_fma_f32 v81, v81, v120, v107
	v_div_scale_f32 v97, vcc, v121, v123, v121
	v_cvt_pk_bf16_f32 v203, v80, v81
	v_fma_f32 v80, -v96, v84, 1.0
	v_fmac_f32_e32 v84, v80, v84
	v_mul_f32_e32 v80, v97, v84
	v_fma_f32 v81, -v96, v80, v97
	v_fmac_f32_e32 v80, v81, v84
	v_fma_f32 v81, -v96, v80, v97
	v_div_fmas_f32 v80, v81, v84, v80
	v_div_fixup_f32 v80, v80, v123, v121
	v_cmp_lt_f32_e32 vcc, 0, v123
	v_fma_f32 v94, v94, v120, v100
	v_fma_f32 v95, v95, v120, v101
	v_fma_f32 v90, v90, v120, v104
	v_fma_f32 v91, v91, v120, v105
	v_cndmask_b32_e32 v80, 0, v80, vcc
	v_fma_f32 v74, v74, v80, v118
	v_fma_f32 v75, v75, v80, v119
	v_fma_f32 v72, v72, v80, v116
	v_fma_f32 v73, v73, v80, v117
	v_cvt_pk_bf16_f32 v198, v74, v75
	v_lshlrev_b32_e32 v74, 16, v178
	v_and_b32_e32 v75, 0xffff0000, v178
	v_fma_f32 v70, v70, v80, v74
	v_fma_f32 v71, v71, v80, v75
	v_cvt_pk_bf16_f32 v199, v72, v73
	v_lshlrev_b32_e32 v72, 16, v179
	v_cvt_pk_bf16_f32 v195, v70, v71
	s_waitcnt vmcnt(1)
	v_lshlrev_b32_e32 v70, 16, v124
	v_and_b32_e32 v73, 0xffff0000, v179
	v_mul_f32_e32 v70, 0xbfb8aa3b, v70
	v_fma_f32 v68, v68, v80, v72
	v_fma_f32 v69, v69, v80, v73
	v_exp_f32_e32 v72, v70
	ds_bpermute_b32 v71, v167, v143
	v_fma_f32 v76, v76, v80, v112
	v_fma_f32 v77, v77, v80, v113
	v_lshlrev_b32_e32 v70, 16, v177
	v_add_f32_e32 v72, 1.0, v72
	v_div_scale_f32 v75, s[0:1], v72, v72, 1.0
	v_cvt_pk_bf16_f32 v201, v76, v77
	s_waitcnt lgkmcnt(0)
	v_add_f32_e32 v73, v143, v71
	v_rcp_f32_e32 v76, v75
	ds_bpermute_b32 v74, v166, v73
	v_and_b32_e32 v71, 0xffff0000, v177
	v_fma_f32 v66, v66, v80, v70
	v_fma_f32 v67, v67, v80, v71
	v_fma_f32 v71, -v75, v76, 1.0
	v_fmac_f32_e32 v76, v71, v76
	v_div_scale_f32 v71, vcc, 1.0, v72, 1.0
	s_waitcnt lgkmcnt(0)
	v_add_f32_e32 v70, v73, v74
	v_mul_f32_e32 v73, v71, v76
	v_fma_f32 v74, -v75, v73, v71
	v_fmac_f32_e32 v73, v74, v76
	v_fma_f32 v71, -v75, v73, v71
	v_div_fmas_f32 v71, v71, v76, v73
	v_div_fixup_f32 v71, v71, v72, 1.0
	v_div_scale_f32 v72, s[0:1], v70, v70, v71
	v_rcp_f32_e32 v73, v72
	v_cvt_pk_bf16_f32 v196, v68, v69
	v_lshlrev_b32_e32 v68, 16, v184
	v_and_b32_e32 v69, 0xffff0000, v184
	v_fma_f32 v64, v64, v80, v68
	v_fma_f32 v65, v65, v80, v69
	v_cvt_pk_bf16_f32 v194, v66, v67
	v_lshlrev_b32_e32 v68, 16, v157
	v_cvt_pk_bf16_f32 v197, v64, v65
	v_fma_f32 v64, -v72, v73, 1.0
	v_fmac_f32_e32 v73, v64, v73
	v_div_scale_f32 v64, vcc, v71, v70, v71
	v_mul_f32_e32 v65, v64, v73
	v_fma_f32 v66, -v72, v65, v64
	v_fmac_f32_e32 v65, v66, v73
	v_fma_f32 v64, -v72, v65, v64
	v_div_fmas_f32 v64, v64, v73, v65
	v_div_fixup_f32 v64, v64, v70, v71
	v_cmp_lt_f32_e32 vcc, 0, v70
	v_and_b32_e32 v69, 0xffff0000, v157
	v_lshlrev_b32_e32 v66, 16, v158
	v_cndmask_b32_e32 v64, 0, v64, vcc
	v_fma_f32 v62, v62, v64, v68
	v_fma_f32 v63, v63, v64, v69
	v_and_b32_e32 v67, 0xffff0000, v158
	v_cvt_pk_bf16_f32 v192, v62, v63
	v_lshlrev_b32_e32 v62, 16, v159
	v_and_b32_e32 v63, 0xffff0000, v159
	v_fma_f32 v58, v58, v64, v62
	v_fma_f32 v59, v59, v64, v63
	v_fma_f32 v60, v60, v64, v66
	v_fma_f32 v61, v61, v64, v67
	v_cvt_pk_bf16_f32 v190, v58, v59
	v_lshlrev_b32_e32 v58, 16, v161
	v_and_b32_e32 v59, 0xffff0000, v161
	v_cvt_pk_bf16_f32 v193, v60, v61
	v_lshlrev_b32_e32 v60, 16, v160
	v_and_b32_e32 v61, 0xffff0000, v160
	v_fma_f32 v54, v54, v64, v58
	v_fma_f32 v55, v55, v64, v59
	v_fma_f32 v56, v56, v64, v60
	v_fma_f32 v57, v57, v64, v61
	v_cvt_pk_bf16_f32 v187, v54, v55
	s_waitcnt vmcnt(0)
	v_lshlrev_b32_e32 v54, 16, v125
	v_cvt_pk_bf16_f32 v191, v56, v57
	v_lshlrev_b32_e32 v56, 16, v174
	v_and_b32_e32 v57, 0xffff0000, v174
	v_mul_f32_e32 v54, 0xbfb8aa3b, v54
	v_fma_f32 v52, v52, v64, v56
	v_fma_f32 v53, v53, v64, v57
	v_exp_f32_e32 v56, v54
	ds_bpermute_b32 v55, v167, v142
	v_lshlrev_b32_e32 v54, 16, v175
	v_cvt_pk_bf16_f32 v188, v52, v53
	v_add_f32_e32 v56, 1.0, v56
	v_div_scale_f32 v59, s[0:1], v56, v56, 1.0
	s_waitcnt lgkmcnt(0)
	v_add_f32_e32 v57, v142, v55
	v_rcp_f32_e32 v60, v59
	ds_bpermute_b32 v58, v166, v57
	v_and_b32_e32 v55, 0xffff0000, v175
	v_fma_f32 v50, v50, v64, v54
	v_fma_f32 v51, v51, v64, v55
	v_fma_f32 v55, -v59, v60, 1.0
	v_fmac_f32_e32 v60, v55, v60
	v_div_scale_f32 v55, vcc, 1.0, v56, 1.0
	s_waitcnt lgkmcnt(0)
	v_add_f32_e32 v54, v57, v58
	v_mul_f32_e32 v57, v55, v60
	v_fma_f32 v58, -v59, v57, v55
	v_fmac_f32_e32 v57, v58, v60
	v_fma_f32 v55, -v59, v57, v55
	v_div_fmas_f32 v55, v55, v60, v57
	v_div_fixup_f32 v55, v55, v56, 1.0
	v_div_scale_f32 v56, s[0:1], v54, v54, v55
	v_rcp_f32_e32 v57, v56
	v_lshlrev_b32_e32 v52, 16, v176
	v_and_b32_e32 v53, 0xffff0000, v176
	v_fma_f32 v48, v48, v64, v52
	v_fma_f32 v49, v49, v64, v53
	v_cvt_pk_bf16_f32 v186, v50, v51
	v_and_b32_e32 v51, 0xffff0000, v155
	v_cvt_pk_bf16_f32 v189, v48, v49
	v_fma_f32 v48, -v56, v57, 1.0
	v_fmac_f32_e32 v57, v48, v57
	v_div_scale_f32 v48, vcc, v55, v54, v55
	v_mul_f32_e32 v49, v48, v57
	v_fma_f32 v50, -v56, v49, v48
	v_fmac_f32_e32 v49, v50, v57
	v_fma_f32 v48, -v56, v49, v48
	v_div_fmas_f32 v48, v48, v57, v49
	v_div_fixup_f32 v48, v48, v54, v55
	v_cmp_lt_f32_e32 vcc, 0, v54
	v_lshlrev_b32_e32 v50, 16, v155
	v_lshlrev_b32_e32 v52, 16, v156
	v_cndmask_b32_e32 v48, 0, v48, vcc
	v_and_b32_e32 v53, 0xffff0000, v156
	v_fma_f32 v46, v46, v48, v52
	v_fma_f32 v47, v47, v48, v53
	v_fma_f32 v44, v44, v48, v50
	v_fma_f32 v45, v45, v48, v51
	v_cvt_pk_bf16_f32 v185, v46, v47
	v_lshlrev_b32_e32 v46, 16, v154
	v_cvt_pk_bf16_f32 v184, v44, v45
	v_lshlrev_b32_e32 v44, 16, v153
	v_and_b32_e32 v45, 0xffff0000, v153
	v_and_b32_e32 v47, 0xffff0000, v154
	v_fma_f32 v42, v42, v48, v46
	v_fma_f32 v43, v43, v48, v47
	v_fma_f32 v40, v40, v48, v44
	v_fma_f32 v41, v41, v48, v45
	v_cvt_pk_bf16_f32 v179, v42, v43
	v_lshlrev_b32_e32 v42, 16, v151
	v_cvt_pk_bf16_f32 v178, v40, v41
	v_lshlrev_b32_e32 v40, 16, v150
	v_and_b32_e32 v41, 0xffff0000, v150
	v_and_b32_e32 v43, 0xffff0000, v151
	s_add_i32 s0, s80, 0xfffffe01
	v_fma_f32 v38, v38, v48, v42
	v_fma_f32 v39, v39, v48, v43
	v_fma_f32 v36, v36, v48, v40
	v_fma_f32 v37, v37, v48, v41
	s_lshr_b32 s0, s0, 5
	v_cvt_pk_bf16_f32 v176, v36, v37
	v_cvt_pk_bf16_f32 v177, v38, v39
	v_lshlrev_b32_e32 v36, 16, v148
	v_and_b32_e32 v37, 0xffff0000, v148
	v_lshlrev_b32_e32 v38, 16, v149
	v_and_b32_e32 v39, 0xffff0000, v149
	s_cmpk_gt_u32 s80, 0x1ff
	v_fma_f32 v88, v88, v120, v98
	v_fma_f32 v89, v89, v120, v99
	v_fma_f32 v86, v86, v120, v108
	v_fma_f32 v87, v87, v120, v109
	v_fma_f32 v82, v82, v120, v110
	v_fma_f32 v83, v83, v120, v111
	v_fma_f32 v78, v78, v80, v114
	v_fma_f32 v79, v79, v80, v115
	v_fma_f32 v34, v34, v48, v38
	v_fma_f32 v35, v35, v48, v39
	v_fma_f32 v32, v32, v48, v36
	v_fma_f32 v33, v33, v48, v37
	s_cselect_b32 s48, s0, 0
	v_cvt_pk_bf16_f32 v209, v92, v93
	v_cvt_pk_bf16_f32 v208, v94, v95
	v_cvt_pk_bf16_f32 v207, v88, v89
	v_cvt_pk_bf16_f32 v206, v90, v91
	v_cvt_pk_bf16_f32 v205, v86, v87
	v_cvt_pk_bf16_f32 v202, v82, v83
	v_cvt_pk_bf16_f32 v200, v78, v79
	v_cvt_pk_bf16_f32 v175, v32, v33
	v_cvt_pk_bf16_f32 v174, v34, v35
	s_cmp_gt_u32 s48, s71
	v_mov_b32_e32 v143, v139
	v_mov_b32_e32 v142, v139
	v_mov_b32_e32 v83, v139
	v_mov_b32_e32 v82, v139
	v_mov_b32_e32 v81, v139
	v_mov_b32_e32 v80, v139
	v_mov_b32_e32 v67, v139
	v_mov_b32_e32 v66, v139
	v_mov_b32_e32 v65, v139
	v_mov_b32_e32 v64, v139
	v_mov_b32_e32 v51, v139
	v_mov_b32_e32 v50, v139
	v_mov_b32_e32 v49, v139
	v_mov_b32_e32 v48, v139
	v_mov_b32_e32 v35, v139
	v_mov_b32_e32 v34, v139
	v_mov_b32_e32 v33, v139
	v_mov_b32_e32 v32, v139
	v_mov_b32_e32 v87, v139
	v_mov_b32_e32 v86, v139
	v_mov_b32_e32 v85, v139
	v_mov_b32_e32 v84, v139
	v_mov_b32_e32 v71, v139
	v_mov_b32_e32 v70, v139
	v_mov_b32_e32 v69, v139
	v_mov_b32_e32 v68, v139
	v_mov_b32_e32 v55, v139
	v_mov_b32_e32 v54, v139
	v_mov_b32_e32 v53, v139
	v_mov_b32_e32 v52, v139
	v_mov_b32_e32 v39, v139
	v_mov_b32_e32 v38, v139
	v_mov_b32_e32 v37, v139
	v_mov_b32_e32 v36, v139
	v_mov_b32_e32 v91, v139
	v_mov_b32_e32 v90, v139
	v_mov_b32_e32 v89, v139
	v_mov_b32_e32 v88, v139
	v_mov_b32_e32 v75, v139
	v_mov_b32_e32 v74, v139
	v_mov_b32_e32 v73, v139
	v_mov_b32_e32 v72, v139
	v_mov_b32_e32 v59, v139
	v_mov_b32_e32 v58, v139
	v_mov_b32_e32 v57, v139
	v_mov_b32_e32 v56, v139
	v_mov_b32_e32 v47, v139
	v_mov_b32_e32 v46, v139
	v_mov_b32_e32 v45, v139
	v_mov_b32_e32 v44, v139
	v_mov_b32_e32 v95, v139
	v_mov_b32_e32 v94, v139
	v_mov_b32_e32 v93, v139
	v_mov_b32_e32 v92, v139
	v_mov_b32_e32 v79, v139
	v_mov_b32_e32 v78, v139
	v_mov_b32_e32 v77, v139
	v_mov_b32_e32 v76, v139
	v_mov_b32_e32 v63, v139
	v_mov_b32_e32 v62, v139
	v_mov_b32_e32 v61, v139
	v_mov_b32_e32 v60, v139
	v_mov_b32_e32 v43, v139
	v_mov_b32_e32 v42, v139
	v_mov_b32_e32 v41, v139
	v_mov_b32_e32 v40, v139
	s_cbranch_scc1 .LBB0_369
	v_add3_u32 v32, s80, -7, v128
	s_add_i32 s0, s48, -1
	v_sub_u32_e32 v32, v32, v130
	s_lshl_b32 s1, s48, 5
	s_lshl_b64 s[6:7], s[48:49], 12
	v_subrev_u32_e32 v210, s1, v32
	v_lshl_add_u64 v[32:33], s[6:7], 0, v[144:145]
	s_add_u32 s6, s87, s76
	v_lshl_add_u64 v[32:33], v[32:33], 0, v[132:133]
	s_addc_u32 s7, s88, s77
	v_mov_b32_e32 v40, 0
	v_add3_u32 v211, v130, s1, 7
	v_lshl_add_u64 v[144:145], s[6:7], 0, v[32:33]
	s_waitcnt vmcnt(0)
	v_lshl_add_u32 v252, v181, 4, s79
	s_add_i32 s98, s79, 0x1000
	s_add_i32 s99, s79, 0x2000
	v_add_co_u32_e32 v250, vcc, 0xfefff400, v144
	s_nop 1
	v_addc_co_u32_e32 v251, vcc, -1, v145, vcc
	v_add_co_u32_e32 v248, vcc, 0xfffff400, v144
	s_nop 1
	v_addc_co_u32_e32 v249, vcc, -1, v145, vcc
	s_mov_b32 m0, s98
	s_nop 0
	global_load_lds_dwordx4 v[250:251], off
	global_load_lds_dwordx4 v[250:251], off offset:1024
	global_load_lds_dwordx4 v[250:251], off offset:2048
	global_load_lds_dwordx4 v[250:251], off offset:3072
	s_mov_b32 m0, s99
	s_nop 0
	global_load_lds_dwordx4 v[248:249], off
	global_load_lds_dwordx4 v[248:249], off offset:1024
	global_load_lds_dwordx4 v[248:249], off offset:2048
	global_load_lds_dwordx4 v[248:249], off offset:3072
	v_mov_b32_e32 v41, v40
	v_mov_b32_e32 v42, v40
	v_mov_b32_e32 v43, v40
	v_mov_b32_e32 v44, v40
	v_mov_b32_e32 v45, v40
	v_mov_b32_e32 v46, v40
	v_mov_b32_e32 v47, v40
	v_mov_b32_e32 v36, v40
	v_mov_b32_e32 v37, v40
	v_mov_b32_e32 v38, v40
	v_mov_b32_e32 v39, v40
	v_mov_b32_e32 v32, v40
	v_mov_b32_e32 v33, v40
	v_mov_b32_e32 v34, v40
	v_mov_b32_e32 v35, v40
	v_mov_b32_e32 v60, v40
	v_mov_b32_e32 v61, v40
	v_mov_b32_e32 v62, v40
	v_mov_b32_e32 v63, v40
	v_mov_b32_e32 v56, v40
	v_mov_b32_e32 v57, v40
	v_mov_b32_e32 v58, v40
	v_mov_b32_e32 v59, v40
	v_mov_b32_e32 v52, v40
	v_mov_b32_e32 v53, v40
	v_mov_b32_e32 v54, v40
	v_mov_b32_e32 v55, v40
	v_mov_b32_e32 v48, v40
	v_mov_b32_e32 v49, v40
	v_mov_b32_e32 v50, v40
	v_mov_b32_e32 v51, v40
	v_mov_b32_e32 v76, v40
	v_mov_b32_e32 v77, v40
	v_mov_b32_e32 v78, v40
	v_mov_b32_e32 v79, v40
	v_mov_b32_e32 v72, v40
	v_mov_b32_e32 v73, v40
	v_mov_b32_e32 v74, v40
	v_mov_b32_e32 v75, v40
	v_mov_b32_e32 v68, v40
	v_mov_b32_e32 v69, v40
	v_mov_b32_e32 v70, v40
	v_mov_b32_e32 v71, v40
	v_mov_b32_e32 v64, v40
	v_mov_b32_e32 v65, v40
	v_mov_b32_e32 v66, v40
	v_mov_b32_e32 v67, v40
	v_mov_b32_e32 v92, v40
	v_mov_b32_e32 v93, v40
	v_mov_b32_e32 v94, v40
	v_mov_b32_e32 v95, v40
	v_mov_b32_e32 v88, v40
	v_mov_b32_e32 v89, v40
	v_mov_b32_e32 v90, v40
	v_mov_b32_e32 v91, v40
	v_mov_b32_e32 v84, v40
	v_mov_b32_e32 v85, v40
	v_mov_b32_e32 v86, v40
	v_mov_b32_e32 v87, v40
	v_mov_b32_e32 v80, v40
	v_mov_b32_e32 v81, v40
	v_mov_b32_e32 v82, v40
	v_mov_b32_e32 v83, v40
	v_mov_b32_e32 v142, v40
	v_mov_b32_e32 v143, v40
	v_mov_b32_e32 v138, v40
	v_mov_b32_e32 v139, v40
